# router phase: packed-FMA dots, streamed weight quads, transpose-reduce; logits handed to lane 0 through SGPRs
# speedup vs baseline: 1.0201x; 1.0071x over previous
; template <int SRC, int EXTRA, bool OUT8 = false> ...
;     ...
;     if (EXTRA != 0) { for (int i = tid; i < 8192; i += NT) { const int k = i >> 3, j = i & 7; w8s[j * 1024 + k] = w8[(size_t)k * w8ld + j]; } if (tid < 8) lcnt[tid] = 0u; __syncthreads(); }
;     f32x4 gv[4], bv[4];
; #pragma unroll
;     for (int j = 0; j < 4; ++j) { gv[j] = *(const f32x4*)(g + 256 * j + 4 * lane); bv[j] = *(const f32x4*)(b + 256 * j + 4 * lane); }
;     const int gw = blockIdx.x * NWAVES + wave, NGW = G * NWAVES;
;     for (int row = gw; row < M; row += NGW) {
.LBB0_1891:
	s_or_b64 exec, exec, s[8:9]
	v_cmp_gt_i32_e64 s[8:9], 8, v48
	v_lshl_add_u32 v49, v48, 2, 0
	s_and_saveexec_b64 s[24:25], s[8:9]
	v_mov_b32_e32 v0, 0
	ds_write_b32 v49, v0 offset:32768
	s_or_b64 exec, exec, s[24:25]
	s_and_b64 vcc, exec, s[4:5]
	s_waitcnt lgkmcnt(0)
	s_barrier
	s_cbranch_vccnz .LBB0_1900
	v_and_b32_e32 v38, 63, v4
	v_lshlrev_b32_e32 v50, 4, v38
	v_mov_b32_e32 v51, 0
	v_lshl_add_u64 v[0:1], s[20:21], 0, v[50:51]
	s_mov_b64 s[20:21], 0x1000
	v_lshl_add_u64 v[32:33], v[0:1], 0, s[20:21]
	v_add_co_u32_e32 v0, vcc, 0x1000, v0
	v_lshl_add_u64 v[4:5], s[22:23], 0, v[50:51]
	s_nop 0
	v_addc_co_u32_e32 v1, vcc, 0, v1, vcc
	v_add_co_u32_e32 v36, vcc, 0x1000, v4
	v_lshl_add_u64 v[34:35], v[4:5], 0, s[20:21]
	s_nop 0
	v_addc_co_u32_e32 v37, vcc, 0, v5, vcc
	global_load_dwordx4 v[0:3], v[0:1], off
	s_nop 0
	global_load_dwordx4 v[4:7], v[36:37], off
	global_load_dwordx4 v[8:11], v[32:33], off offset:1024
	global_load_dwordx4 v[12:15], v[32:33], off offset:2048
	global_load_dwordx4 v[16:19], v[34:35], off offset:1024
	global_load_dwordx4 v[20:23], v[34:35], off offset:2048
	global_load_dwordx4 v[24:27], v[32:33], off offset:3072
	global_load_dwordx4 v[28:31], v[34:35], off offset:3072
	s_add_u32 s3, s10, 0x400000
	s_addc_u32 s50, s11, 0
	s_add_u32 s51, s18, 0x340000
	s_addc_u32 s52, s19, 0
	s_lshl_b32 s18, s2, 4
	s_lshl_b32 s19, s68, 1
	s_ashr_i32 s35, s34, 31
	s_add_i32 s38, s18, s19
	s_lshl_b32 s53, s33, 4
	s_lshl_b64 s[18:19], s[34:35], 2
	s_add_u32 s16, s16, s18
	s_addc_u32 s17, s17, s19
	s_add_u32 s40, s16, 0x300000
	s_addc_u32 s41, s17, 0
	s_ashr_i32 s31, s30, 31
	s_lshl_b64 s[42:43], s[30:31], 2
	s_lshl_b64 s[16:17], s[34:35], 11
	s_add_u32 s14, s14, s16
	v_lshlrev_b32_e32 v32, 3, v38
	v_mov_b32_e32 v33, v51
	s_addc_u32 s15, s15, s17
	v_lshl_add_u64 v[32:33], s[14:15], 0, v[32:33]
	s_mov_b64 s[14:15], 0x12500600
	v_lshl_add_u64 v[52:53], v[32:33], 0, s[14:15]
	s_lshl_b64 s[44:45], s[30:31], 11
	s_lshl_b64 s[14:15], s[34:35], 12
	s_add_u32 s12, s12, s14
	s_addc_u32 s13, s13, s15
	v_lshl_add_u64 v[32:33], s[12:13], 0, v[50:51]
	s_mov_b64 s[12:13], 0x28500c00
	v_cmp_eq_u32_e64 s[10:11], 0, v38
	v_lshl_add_u64 v[54:55], v[32:33], 0, s[12:13]
	s_lshl_b64 s[46:47], s[30:31], 12
	v_mov_b32_e32 v61, 0x3727c5ac
	s_mov_b32 s31, 0xf800000
	v_mov_b32_e32 v62, 0x260
	s_movk_i32 s35, 0x7fff
	s_mov_b32 s54, 0xffff0000
	v_mov_b32_e32 v63, 1
	s_mov_b32 s55, 0xff800000
	v_mov_b32_e32 v64, 0xff800000
	s_mov_b32 s56, s34
	global_load_dwordx4 v[200:203], v[54:55], off offset:-3072
	global_load_dwordx4 v[196:199], v[54:55], off offset:-2048
	global_load_dwordx4 v[192:195], v[54:55], off offset:-1024
	global_load_dwordx4 v[188:191], v[54:55], off
	s_waitcnt vmcnt(0)
	s_mov_b32 s58, 0xaaaaaaaa
	s_mov_b32 s59, 0xaaaaaaaa
	s_mov_b32 s60, 0xcccccccc
	s_mov_b32 s61, 0xcccccccc
	s_mov_b32 s62, 0xf0f0f0f0
	s_mov_b32 s63, 0xf0f0f0f0
	s_branch .LBB0_1896

; template <int SRC, int EXTRA, bool OUT8 = false> ...
;     ...
;         float s = 0.f;
; #pragma unroll
;         for (int j = 0; j < 4; ++j) s += (v[j].x + v[j].y) + (v[j].z + v[j].w);
;         const float mean = wave_sum(s) * (1.f / 1024.f); float s2 = 0.f;
; #pragma unroll
;         for (int j = 0; j < 4; ++j) { v[j] = v[j] - mean; s2 += (v[j].x * v[j].x + v[j].y * v[j].y) + (v[j].z * v[j].z + v[j].w * v[j].w); }
;         const float rstd = 1.f / sqrtf(wave_sum(s2) * (1.f / 1024.f) + LN_EPS);
;         if (stats && lane == 0) { stats[2 * row] = mean; stats[2 * row + 1] = rstd; }
.Lrowpf_48034:
	s_waitcnt lgkmcnt(0)
	ds_read_b128 v[124:127], v50
	ds_read_b128 v[128:131], v50 offset:1024
	ds_read_b128 v[132:135], v50 offset:2048
	ds_read_b128 v[136:139], v50 offset:3072
	ds_read_b128 v[140:143], v50 offset:4096
	ds_read_b128 v[144:147], v50 offset:5120
	ds_read_b128 v[148:151], v50 offset:6144
	ds_read_b128 v[152:155], v50 offset:7168
	ds_read_b128 v[156:159], v50 offset:8192
	ds_read_b128 v[160:163], v50 offset:9216
	ds_read_b128 v[164:167], v50 offset:10240
	ds_read_b128 v[168:171], v50 offset:11264
	ds_read_b128 v[172:175], v50 offset:12288
	ds_read_b128 v[176:179], v50 offset:13312
	ds_read_b128 v[180:183], v50 offset:14336
	ds_read_b128 v[184:187], v50 offset:15360
	v_mov_b32_e32 v57, v46
	v_mov_b32_e32 v56, v45
	v_mov_b32_e32 v58, v44
	v_mov_b32_e32 v59, v47
	v_mov_b32_e32 v66, v41
	v_mov_b32_e32 v67, v42
	v_mov_b32_e32 v68, v40
	v_mov_b32_e32 v69, v43
	v_pk_add_f32 v[56:57], v[56:57], v[58:59]
	v_pk_add_f32 v[58:59], v[66:67], v[68:69]
	v_add_f32_e32 v65, v56, v57
	v_pk_add_f32 v[56:57], v[58:59], v[58:59] op_sel:[0,1] op_sel_hi:[1,0]
	v_add_f32_e32 v70, v36, v37
	v_add_f32_e32 v72, v38, v39
	v_mov_b32_e32 v75, v32
	v_mov_b32_e32 v71, v34
	v_mov_b32_e32 v73, v35
	v_add_f32_e32 v74, 0, v65
	v_mov_b32_e32 v57, v33
	v_pk_add_f32 v[66:67], v[70:71], v[72:73]
	v_pk_add_f32 v[56:57], v[74:75], v[56:57]
	s_nop 0
	v_pk_add_f32 v[56:57], v[56:57], v[66:67]
	v_add_f32_e32 v56, v56, v57
	s_nop 1
	v_mov_b32_dpp v57, v56 quad_perm:[1,0,3,2] row_mask:0xf bank_mask:0xf
	v_add_f32_e32 v56, v56, v57
	s_nop 1
	v_mov_b32_dpp v57, v56 quad_perm:[2,3,0,1] row_mask:0xf bank_mask:0xf
	v_add_f32_e32 v56, v56, v57
	s_nop 1
	v_mov_b32_dpp v57, v56 row_shl:4 row_mask:0xf bank_mask:0x5
	v_mov_b32_dpp v57, v56 row_shr:4 row_mask:0xf bank_mask:0xa
	v_add_f32_e32 v56, v56, v57
	s_nop 1
	v_mov_b32_dpp v57, v56 row_ror:8 row_mask:0xf bank_mask:0xf
	v_add_f32_e32 v56, v56, v57
	v_mov_b32_e32 v57, v56
	v_mov_b32_e32 v120, v56
	s_nop 1
	v_permlane16_swap_b32_e32 v57, v120
	v_cndmask_b32_e64 v57, v120, v57, s[98:99]
	v_add_f32_e32 v56, v56, v57
	v_mov_b32_e32 v57, v56
	v_mov_b32_e32 v120, v56
	s_nop 1
	v_permlane32_swap_b32_e32 v57, v120
	v_cndmask_b32_e64 v57, v120, v57, s[100:101]
	v_add_f32_e32 v65, v56, v57
	v_fmamk_f32 v59, v65, 0xba800000, v47
	v_fmamk_f32 v45, v65, 0xba800000, v45
	v_fmamk_f32 v43, v65, 0xba800000, v43
	v_fmamk_f32 v41, v65, 0xba800000, v41
	v_fmamk_f32 v58, v65, 0xba800000, v46
	v_fmac_f32_e32 v44, 0xba800000, v65
	v_fmamk_f32 v42, v65, 0xba800000, v42
	v_fmac_f32_e32 v40, 0xba800000, v65
	v_fmamk_f32 v57, v65, 0xba800000, v39
	v_fmamk_f32 v56, v65, 0xba800000, v38
	v_fmamk_f32 v37, v65, 0xba800000, v37
	v_fmamk_f32 v47, v65, 0xba800000, v35
	v_fmamk_f32 v46, v65, 0xba800000, v34
	v_mul_f32_e32 v34, v45, v45
	v_mul_f32_e32 v35, v59, v59
	v_mul_f32_e32 v38, v41, v41
	v_mul_f32_e32 v39, v43, v43
	v_fmac_f32_e32 v36, 0xba800000, v65
	v_fmamk_f32 v33, v65, 0xba800000, v33
	v_mul_f32_e32 v66, v37, v37
	v_mul_f32_e32 v67, v57, v57
	v_fmac_f32_e32 v34, v44, v44
	v_fmac_f32_e32 v35, v58, v58
	v_fmac_f32_e32 v38, v40, v40
	v_fmac_f32_e32 v39, v42, v42
	v_fmac_f32_e32 v32, 0xba800000, v65
	v_mul_f32_e32 v68, v33, v33
	v_mul_f32_e32 v69, v47, v47
	v_fmac_f32_e32 v66, v36, v36
	v_fmac_f32_e32 v67, v56, v56
	v_add_f32_e32 v34, v34, v35
	v_add_f32_e32 v35, v38, v39
	v_fmac_f32_e32 v68, v32, v32
	v_fmac_f32_e32 v69, v46, v46
	v_add_f32_e32 v38, v66, v67
	v_add_f32_e32 v34, v34, v35
	v_add_f32_e32 v39, v68, v69
	v_add_f32_e32 v34, v38, v34
	v_add_f32_e32 v34, v39, v34
	s_nop 1
	v_mov_b32_dpp v35, v34 quad_perm:[1,0,3,2] row_mask:0xf bank_mask:0xf
	v_add_f32_e32 v34, v34, v35
	s_nop 1
	v_mov_b32_dpp v35, v34 quad_perm:[2,3,0,1] row_mask:0xf bank_mask:0xf
	v_add_f32_e32 v34, v34, v35
	s_nop 1
	v_mov_b32_dpp v35, v34 row_shl:4 row_mask:0xf bank_mask:0x5
	v_mov_b32_dpp v35, v34 row_shr:4 row_mask:0xf bank_mask:0xa
	v_add_f32_e32 v34, v34, v35
	s_nop 1
	v_mov_b32_dpp v35, v34 row_ror:8 row_mask:0xf bank_mask:0xf
	v_add_f32_e32 v34, v34, v35
	v_mov_b32_e32 v35, v34
	v_mov_b32_e32 v120, v34
	s_nop 1
	v_permlane16_swap_b32_e32 v35, v120
	v_cndmask_b32_e64 v35, v120, v35, s[98:99]
	v_add_f32_e32 v34, v34, v35
	v_mov_b32_e32 v35, v34
	v_mov_b32_e32 v120, v34
	s_nop 1
	v_permlane32_swap_b32_e32 v35, v120
	v_cndmask_b32_e64 v35, v120, v35, s[100:101]
	v_add_f32_e32 v34, v34, v35
	v_fmamk_f32 v34, v34, 0x3a800000, v61
	v_mul_f32_e32 v35, 0x4f800000, v34
	v_cmp_gt_f32_e32 vcc, s31, v34
	s_nop 1
	v_cndmask_b32_e32 v34, v34, v35, vcc
	v_sqrt_f32_e32 v35, v34
	s_nop 0
	v_add_u32_e32 v38, -1, v35
	v_add_u32_e32 v39, 1, v35
	v_fma_f32 v60, -v38, v35, v34
	v_fma_f32 v66, -v39, v35, v34
	v_cmp_ge_f32_e64 s[12:13], 0, v60
	s_nop 1
	v_cndmask_b32_e64 v35, v35, v38, s[12:13]
	v_cmp_lt_f32_e64 s[12:13], 0, v66
	s_nop 1
	v_cndmask_b32_e64 v35, v35, v39, s[12:13]
	v_mul_f32_e32 v38, 0x37800000, v35
	v_cndmask_b32_e32 v35, v35, v38, vcc
	v_cmp_class_f32_e32 vcc, v34, v62
	s_nop 1
	v_cndmask_b32_e32 v34, v35, v34, vcc
	v_div_scale_f32 v35, s[12:13], v34, v34, 1.0
	v_rcp_f32_e32 v38, v35
	v_div_scale_f32 v39, vcc, 1.0, v34, 1.0
	v_fma_f32 v60, -v35, v38, 1.0
	v_fmac_f32_e32 v38, v60, v38
	v_mul_f32_e32 v60, v39, v38
	v_fma_f32 v66, -v35, v60, v39
	v_fmac_f32_e32 v60, v66, v38
	v_fma_f32 v35, -v35, v60, v39
	v_div_fmas_f32 v35, v35, v38, v60
	v_div_fixup_f32 v60, v35, v34, 1.0
	s_and_saveexec_b64 s[12:13], s[10:11]
	s_cbranch_execz .LBB0_1898
	s_ashr_i32 s39, s38, 31
	s_lshl_b64 s[14:15], s[38:39], 2
	s_add_u32 s14, s3, s14
	v_mul_f32_e32 v34, 0x3a800000, v65
	s_addc_u32 s15, s50, s15
	v_mov_b32_e32 v35, v60
	global_store_dwordx2 v51, v[34:35], s[14:15]
; #define LAS __attribute__((address_space(3)))
; __device__ __forceinline__ unsigned pk2(float lo, float hi) { return f2bf(lo) | (f2bf(hi) << 16); }
; template <int SRC, int EXTRA, bool OUT8 = false> ...
;     ...
;         for (int j = 0; j < 4; ++j) { v[j] = v[j] * rstd * gv[j] + bv[j]; if (of32) *(f32x4*)(of32 + (size_t)row * 1024 + 256 * j + 4 * lane) = v[j];
;             if (obf) { if constexpr (OUT8) { int w = 0; w = __builtin_amdgcn_cvt_pk_fp8_f32(v[j].x, v[j].y, w, false); w = __builtin_amdgcn_cvt_pk_fp8_f32(v[j].z, v[j].w, w, true); *(unsigned*)((unsigned char*)obf + (size_t)row * 1024 + 256 * j + 4 * lane) = (unsigned)w; }
;                 else { v2u o; o.x = pk2(v[j].x, v[j].y); o.y = pk2(v[j].z, v[j].w); *(v2u*)(obf + (size_t)row * 1024 + 256 * j + 4 * lane) = o; } } }
;         if (EXTRA != 0) {
;             float d[8];
; #pragma unroll
;             for (int e = 0; e < 8; ++e) { float a = 0.f;
; #pragma unroll
;                 for (int j = 0; j < 4; ++j) { const f32x4 w = *(const LAS f32x4*)(w8s + e * 1024 + 256 * j + 4 * lane); a += (v[j].x * w.x + v[j].y * w.y) + (v[j].z * w.z + v[j].w * w.w); }
.LBB0_1898:
	s_or_b64 exec, exec, s[12:13]
	v_pk_mul_f32 v[38:39], v[44:45], v[60:61] op_sel_hi:[1,0]
	v_pk_mul_f32 v[34:35], v[58:59], v[60:61] op_sel_hi:[1,0]
	v_pk_fma_f32 v[38:39], v[0:1], v[38:39], v[4:5]
	v_pk_fma_f32 v[34:35], v[2:3], v[34:35], v[6:7]
	v_bfe_u32 v44, v38, 16, 1
	v_add3_u32 v44, v38, v44, s35
	v_bfe_u32 v45, v39, 16, 1
	v_lshrrev_b32_e32 v44, 16, v44
	v_add3_u32 v45, v39, v45, s35
	v_and_or_b32 v44, v45, s54, v44
	v_bfe_u32 v45, v34, 16, 1
	v_add3_u32 v45, v34, v45, s35
	v_bfe_u32 v58, v35, 16, 1
	v_lshrrev_b32_e32 v45, 16, v45
	v_add3_u32 v58, v35, v58, s35
	v_and_or_b32 v45, v58, s54, v45
	global_store_dwordx2 v[52:53], v[44:45], off offset:-1536
	v_pk_mul_f32 v[42:43], v[42:43], v[60:61] op_sel_hi:[1,0]
	v_pk_mul_f32 v[44:45], v[40:41], v[60:61] op_sel_hi:[1,0]
	v_pk_fma_f32 v[40:41], v[10:11], v[42:43], v[18:19]
	v_pk_fma_f32 v[42:43], v[8:9], v[44:45], v[16:17]
	v_bfe_u32 v58, v41, 16, 1
	v_bfe_u32 v44, v42, 16, 1
	v_add3_u32 v44, v42, v44, s35
	v_bfe_u32 v45, v43, 16, 1
	v_lshrrev_b32_e32 v44, 16, v44
	v_add3_u32 v45, v43, v45, s35
	v_and_or_b32 v44, v45, s54, v44
	v_bfe_u32 v45, v40, 16, 1
	v_add3_u32 v45, v40, v45, s35
	v_lshrrev_b32_e32 v45, 16, v45
	v_add3_u32 v58, v41, v58, s35
	v_and_or_b32 v45, v58, s54, v45
	global_store_dwordx2 v[52:53], v[44:45], off offset:-1024
	v_pk_mul_f32 v[44:45], v[56:57], v[60:61] op_sel_hi:[1,0]
	v_pk_mul_f32 v[56:57], v[36:37], v[60:61] op_sel_hi:[1,0]
	v_pk_fma_f32 v[36:37], v[14:15], v[44:45], v[22:23]
	v_pk_fma_f32 v[44:45], v[12:13], v[56:57], v[20:21]
	v_bfe_u32 v58, v37, 16, 1
	v_bfe_u32 v56, v44, 16, 1
	v_add3_u32 v56, v44, v56, s35
	v_bfe_u32 v57, v45, 16, 1
	v_lshrrev_b32_e32 v56, 16, v56
	v_add3_u32 v57, v45, v57, s35
	v_and_or_b32 v56, v57, s54, v56
	v_bfe_u32 v57, v36, 16, 1
	v_add3_u32 v57, v36, v57, s35
	v_lshrrev_b32_e32 v57, 16, v57
	v_add3_u32 v58, v37, v58, s35
	v_and_or_b32 v57, v58, s54, v57
	global_store_dwordx2 v[52:53], v[56:57], off offset:-512
	v_pk_mul_f32 v[46:47], v[46:47], v[60:61] op_sel_hi:[1,0]
	v_pk_mul_f32 v[56:57], v[32:33], v[60:61] op_sel_hi:[1,0]
	v_pk_fma_f32 v[32:33], v[26:27], v[46:47], v[30:31]
	v_pk_fma_f32 v[46:47], v[24:25], v[56:57], v[28:29]
	v_bfe_u32 v58, v33, 16, 1
	v_bfe_u32 v56, v46, 16, 1
	v_add3_u32 v56, v46, v56, s35
	v_bfe_u32 v57, v47, 16, 1
	v_lshrrev_b32_e32 v56, 16, v56
	v_add3_u32 v57, v47, v57, s35
	v_and_or_b32 v56, v57, s54, v56
	v_bfe_u32 v57, v32, 16, 1
	v_add3_u32 v57, v32, v57, s35
	v_lshrrev_b32_e32 v57, 16, v57
	v_add3_u32 v58, v33, v58, s35
	v_and_or_b32 v57, v58, s54, v57
	global_store_dwordx2 v[52:53], v[56:57], off
	s_waitcnt lgkmcnt(0)
	v_pk_mul_f32 v[216:217], v[38:39], v[124:125]
	v_pk_mul_f32 v[218:219], v[38:39], v[140:141]
	v_pk_mul_f32 v[220:221], v[38:39], v[156:157]
	v_pk_mul_f32 v[222:223], v[38:39], v[172:173]
	v_pk_fma_f32 v[216:217], v[34:35], v[126:127], v[216:217]
	v_pk_fma_f32 v[218:219], v[34:35], v[142:143], v[218:219]
	v_pk_fma_f32 v[220:221], v[34:35], v[158:159], v[220:221]
	v_pk_fma_f32 v[222:223], v[34:35], v[174:175], v[222:223]
	ds_read_b128 v[124:127], v50 offset:16384
	ds_read_b128 v[140:143], v50 offset:20480
	ds_read_b128 v[156:159], v50 offset:24576
	ds_read_b128 v[172:175], v50 offset:28672
	v_pk_fma_f32 v[216:217], v[42:43], v[128:129], v[216:217]
	v_pk_fma_f32 v[218:219], v[42:43], v[144:145], v[218:219]
	v_pk_fma_f32 v[220:221], v[42:43], v[160:161], v[220:221]
	v_pk_fma_f32 v[222:223], v[42:43], v[176:177], v[222:223]
	v_pk_fma_f32 v[216:217], v[40:41], v[130:131], v[216:217]
	v_pk_fma_f32 v[218:219], v[40:41], v[146:147], v[218:219]
	v_pk_fma_f32 v[220:221], v[40:41], v[162:163], v[220:221]
	v_pk_fma_f32 v[222:223], v[40:41], v[178:179], v[222:223]
	ds_read_b128 v[128:131], v50 offset:17408
	ds_read_b128 v[144:147], v50 offset:21504
	ds_read_b128 v[160:163], v50 offset:25600
	ds_read_b128 v[176:179], v50 offset:29696
	v_pk_fma_f32 v[216:217], v[44:45], v[132:133], v[216:217]
	v_pk_fma_f32 v[218:219], v[44:45], v[148:149], v[218:219]
	v_pk_fma_f32 v[220:221], v[44:45], v[164:165], v[220:221]
	v_pk_fma_f32 v[222:223], v[44:45], v[180:181], v[222:223]
	v_pk_fma_f32 v[216:217], v[36:37], v[134:135], v[216:217]
	v_pk_fma_f32 v[218:219], v[36:37], v[150:151], v[218:219]
	v_pk_fma_f32 v[220:221], v[36:37], v[166:167], v[220:221]
	v_pk_fma_f32 v[222:223], v[36:37], v[182:183], v[222:223]
	ds_read_b128 v[132:135], v50 offset:18432
	ds_read_b128 v[148:151], v50 offset:22528
	ds_read_b128 v[164:167], v50 offset:26624
	ds_read_b128 v[180:183], v50 offset:30720
	v_pk_fma_f32 v[216:217], v[46:47], v[136:137], v[216:217]
	v_pk_fma_f32 v[218:219], v[46:47], v[152:153], v[218:219]
	v_pk_fma_f32 v[220:221], v[46:47], v[168:169], v[220:221]
	v_pk_fma_f32 v[222:223], v[46:47], v[184:185], v[222:223]
	v_pk_fma_f32 v[216:217], v[32:33], v[138:139], v[216:217]
	v_pk_fma_f32 v[218:219], v[32:33], v[154:155], v[218:219]
	v_pk_fma_f32 v[220:221], v[32:33], v[170:171], v[220:221]
	v_pk_fma_f32 v[222:223], v[32:33], v[186:187], v[222:223]
	ds_read_b128 v[136:139], v50 offset:19456
	ds_read_b128 v[152:155], v50 offset:23552
	ds_read_b128 v[168:171], v50 offset:27648
	ds_read_b128 v[184:187], v50 offset:31744
	v_add_f32_e32 v208, v216, v217
	v_add_f32_e32 v209, v218, v219
	v_add_f32_e32 v210, v220, v221
	v_add_f32_e32 v211, v222, v223
	s_waitcnt lgkmcnt(12)
	v_pk_mul_f32 v[216:217], v[38:39], v[124:125]
	v_pk_mul_f32 v[218:219], v[38:39], v[140:141]
	v_pk_mul_f32 v[220:221], v[38:39], v[156:157]
	v_pk_mul_f32 v[222:223], v[38:39], v[172:173]
	v_pk_fma_f32 v[216:217], v[34:35], v[126:127], v[216:217]
	v_pk_fma_f32 v[218:219], v[34:35], v[142:143], v[218:219]
	v_pk_fma_f32 v[220:221], v[34:35], v[158:159], v[220:221]
	v_pk_fma_f32 v[222:223], v[34:35], v[174:175], v[222:223]
	s_waitcnt lgkmcnt(8)
; #define LAS __attribute__((address_space(3)))
; template <int SRC, int EXTRA, bool OUT8 = false> ...
;     ...
;             for (int e = 0; e < 8; ++e) { float a = 0.f;
; #pragma unroll
;                 for (int j = 0; j < 4; ++j) { const f32x4 w = *(const LAS f32x4*)(w8s + e * 1024 + 256 * j + 4 * lane); a += (v[j].x * w.x + v[j].y * w.y) + (v[j].z * w.z + v[j].w * w.w); }
;                 d[e] = wave_sum(a); }
	v_pk_fma_f32 v[216:217], v[42:43], v[128:129], v[216:217]
	v_pk_fma_f32 v[218:219], v[42:43], v[144:145], v[218:219]
	v_pk_fma_f32 v[220:221], v[42:43], v[160:161], v[220:221]
	v_pk_fma_f32 v[222:223], v[42:43], v[176:177], v[222:223]
	v_pk_fma_f32 v[216:217], v[40:41], v[130:131], v[216:217]
	v_pk_fma_f32 v[218:219], v[40:41], v[146:147], v[218:219]
	v_pk_fma_f32 v[220:221], v[40:41], v[162:163], v[220:221]
	v_pk_fma_f32 v[222:223], v[40:41], v[178:179], v[222:223]
	s_waitcnt lgkmcnt(4)
	v_pk_fma_f32 v[216:217], v[44:45], v[132:133], v[216:217]
	v_pk_fma_f32 v[218:219], v[44:45], v[148:149], v[218:219]
	v_pk_fma_f32 v[220:221], v[44:45], v[164:165], v[220:221]
	v_pk_fma_f32 v[222:223], v[44:45], v[180:181], v[222:223]
	v_pk_fma_f32 v[216:217], v[36:37], v[134:135], v[216:217]
	v_pk_fma_f32 v[218:219], v[36:37], v[150:151], v[218:219]
	v_pk_fma_f32 v[220:221], v[36:37], v[166:167], v[220:221]
	v_pk_fma_f32 v[222:223], v[36:37], v[182:183], v[222:223]
	s_waitcnt lgkmcnt(0)
	v_pk_fma_f32 v[216:217], v[46:47], v[136:137], v[216:217]
	v_pk_fma_f32 v[218:219], v[46:47], v[152:153], v[218:219]
	v_pk_fma_f32 v[220:221], v[46:47], v[168:169], v[220:221]
	v_pk_fma_f32 v[222:223], v[46:47], v[184:185], v[222:223]
	v_pk_fma_f32 v[216:217], v[32:33], v[138:139], v[216:217]
	v_pk_fma_f32 v[218:219], v[32:33], v[154:155], v[218:219]
	v_pk_fma_f32 v[220:221], v[32:33], v[170:171], v[220:221]
	v_pk_fma_f32 v[222:223], v[32:33], v[186:187], v[222:223]
	v_add_f32_e32 v212, v216, v217
	v_add_f32_e32 v213, v218, v219
	v_add_f32_e32 v214, v220, v221
	v_add_f32_e32 v215, v222, v223
	s_nop 0
	v_add_f32_dpp v216, v208, v208 quad_perm:[1,0,3,2] row_mask:0xf bank_mask:0xf
	v_add_f32_dpp v217, v209, v209 quad_perm:[1,0,3,2] row_mask:0xf bank_mask:0xf
	v_cndmask_b32_e64 v224, v216, v217, s[58:59]
	v_add_f32_dpp v218, v210, v210 quad_perm:[1,0,3,2] row_mask:0xf bank_mask:0xf
	v_add_f32_dpp v219, v211, v211 quad_perm:[1,0,3,2] row_mask:0xf bank_mask:0xf
	v_cndmask_b32_e64 v225, v218, v219, s[58:59]
	v_add_f32_dpp v220, v212, v212 quad_perm:[1,0,3,2] row_mask:0xf bank_mask:0xf
	v_add_f32_dpp v221, v213, v213 quad_perm:[1,0,3,2] row_mask:0xf bank_mask:0xf
	v_cndmask_b32_e64 v226, v220, v221, s[58:59]
	v_add_f32_dpp v222, v214, v214 quad_perm:[1,0,3,2] row_mask:0xf bank_mask:0xf
	v_add_f32_dpp v223, v215, v215 quad_perm:[1,0,3,2] row_mask:0xf bank_mask:0xf
	v_cndmask_b32_e64 v227, v222, v223, s[58:59]
	v_add_f32_dpp v216, v224, v224 quad_perm:[2,3,0,1] row_mask:0xf bank_mask:0xf
	v_add_f32_dpp v217, v225, v225 quad_perm:[2,3,0,1] row_mask:0xf bank_mask:0xf
	v_cndmask_b32_e64 v228, v216, v217, s[60:61]
	v_add_f32_dpp v218, v226, v226 quad_perm:[2,3,0,1] row_mask:0xf bank_mask:0xf
	v_add_f32_dpp v219, v227, v227 quad_perm:[2,3,0,1] row_mask:0xf bank_mask:0xf
	v_cndmask_b32_e64 v229, v218, v219, s[60:61]
	v_add_f32_dpp v216, v228, v228 row_shl:4 row_mask:0xf bank_mask:0x5
	v_add_f32_dpp v216, v228, v228 row_shr:4 row_mask:0xf bank_mask:0xa
	v_add_f32_dpp v217, v229, v229 row_shl:4 row_mask:0xf bank_mask:0x5
	v_add_f32_dpp v217, v229, v229 row_shr:4 row_mask:0xf bank_mask:0xa
	v_cndmask_b32_e64 v230, v216, v217, s[62:63]
	s_nop 1
	v_add_f32_dpp v231, v230, v230 row_ror:8 row_mask:0xf bank_mask:0xf
	v_mov_b32_e32 v216, v231
	v_mov_b32_e32 v120, v231
	s_nop 1
	v_permlane16_swap_b32_e32 v216, v120
	v_cndmask_b32_e64 v216, v120, v216, s[98:99]
	v_add_f32_e32 v231, v231, v216
	v_mov_b32_e32 v216, v231
	v_mov_b32_e32 v120, v231
	s_nop 1
	v_permlane32_swap_b32_e32 v216, v120
	v_cndmask_b32_e64 v216, v120, v216, s[100:101]
	v_add_f32_e32 v232, v231, v216
	s_nop 1
	v_readlane_b32 s80, v232, 0
	v_readlane_b32 s81, v232, 1
	v_readlane_b32 s82, v232, 2
	v_readlane_b32 s83, v232, 3
	v_readlane_b32 s84, v232, 4
	v_readlane_b32 s85, v232, 5
	v_readlane_b32 s86, v232, 6
	v_readlane_b32 s87, v232, 7
	s_nop 1
	s_and_saveexec_b64 s[48:49], s[10:11]
	s_cbranch_execz .LBB0_1895
; template <int SRC, int EXTRA, bool OUT8 = false> ...
;     ...
;             } else {
;                 int i0 = 0; float v0 = d[0];
; #pragma unroll
;                 for (int e = 1; e < 8; ++e) if (d[e] > v0) { v0 = d[e]; i0 = e; }
;                 int i1 = -1; float v1 = -INFINITY;
; #pragma unroll
;                 for (int e = 0; e < 8; ++e) if (e != i0 && d[e] > v1) { v1 = d[e]; i1 = e; }
;                 if (lane == 0) { const float w0 = 1.f / (1.f + __expf(v1 - v0)); eidx[row] = i0 | (i1 << 8); gwout[2 * row] = w0; gwout[2 * row + 1] = 1.f - w0;
;                     atomicAdd((unsigned*)&lcnt[i0], 1u); atomicAdd((unsigned*)&lcnt[i1], 1u); }
	v_mov_b32_e32 v34, s87
	v_mov_b32_e32 v35, s86
	v_mov_b32_e32 v32, s81
	v_mov_b32_e32 v33, s80
	v_mov_b32_e32 v39, s82
	v_cmp_gt_f32_e32 vcc, v32, v33
	v_mov_b32_e32 v38, s83
	v_mov_b32_e32 v37, s84
	v_cndmask_b32_e32 v40, v33, v32, vcc
	v_cmp_gt_f32_e64 s[12:13], v39, v40
	v_mov_b32_e32 v36, s85
	v_cndmask_b32_e64 v41, 0, 1, vcc
	v_cndmask_b32_e64 v40, v40, v39, s[12:13]
	v_cmp_gt_f32_e64 s[14:15], v38, v40
	v_cndmask_b32_e64 v41, v41, 2, s[12:13]
	v_cmp_nlg_f32_e64 s[24:25], s55, v33
	v_cndmask_b32_e64 v40, v40, v38, s[14:15]
	v_cmp_gt_f32_e64 s[16:17], v37, v40
	v_cndmask_b32_e64 v41, v41, 3, s[14:15]
	s_ashr_i32 s39, s38, 31
	v_cndmask_b32_e64 v40, v40, v37, s[16:17]
	v_cmp_gt_f32_e64 s[18:19], v36, v40
	v_cndmask_b32_e64 v41, v41, 4, s[16:17]
	s_nop 0
	v_cndmask_b32_e64 v40, v40, v36, s[18:19]
	v_cmp_gt_f32_e64 s[20:21], v35, v40
	v_cndmask_b32_e64 v41, v41, 5, s[18:19]
	s_nop 0
	v_cndmask_b32_e64 v40, v40, v35, s[20:21]
	v_cndmask_b32_e64 v41, v41, 6, s[20:21]
	v_cmp_ngt_f32_e32 vcc, v34, v40
	s_and_b64 s[26:27], s[20:21], vcc
	s_nop 0
	v_cndmask_b32_e32 v41, 7, v41, vcc
	v_cmp_eq_u32_e64 s[22:23], 0, v41
	s_or_b64 s[22:23], s[22:23], s[24:25]
	v_cmp_ne_u32_e64 s[20:21], 1, v41
	v_cndmask_b32_e64 v33, v33, v64, s[22:23]
	v_cmp_gt_f32_e64 s[24:25], v32, v33
	s_and_b64 s[20:21], s[20:21], s[24:25]
	v_cndmask_b32_e64 v32, v33, v32, s[20:21]
	v_cmp_ne_u32_e64 s[18:19], 2, v41
	v_cmp_gt_f32_e64 s[24:25], v39, v32
	s_and_b64 s[18:19], s[18:19], s[24:25]
	v_cndmask_b32_e64 v32, v32, v39, s[18:19]
	v_cmp_ne_u32_e64 s[16:17], 3, v41
	v_cmp_gt_f32_e64 s[24:25], v38, v32
	s_and_b64 s[16:17], s[16:17], s[24:25]
	v_cndmask_b32_e64 v32, v32, v38, s[16:17]
	v_cmp_ne_u32_e64 s[14:15], 4, v41
	v_cmp_gt_f32_e64 s[24:25], v37, v32
	s_and_b64 s[14:15], s[14:15], s[24:25]
	v_cndmask_b32_e64 v32, v32, v37, s[14:15]
	v_cmp_ne_u32_e64 s[12:13], 5, v41
	v_cmp_gt_f32_e64 s[24:25], v36, v32
	s_and_b64 s[12:13], s[12:13], s[24:25]
	v_cndmask_b32_e64 v32, v32, v36, s[12:13]
	v_cmp_ngt_f32_e64 s[24:25], v35, v32
	s_or_b64 s[24:25], s[26:27], s[24:25]
	v_cndmask_b32_e64 v33, 0, -1, s[22:23]
	v_cndmask_b32_e64 v32, v35, v32, s[24:25]
	v_cmp_gt_f32_e64 s[26:27], v34, v32
	s_and_b64 s[26:27], vcc, s[26:27]
	v_cndmask_b32_e64 v33, v33, 1, s[20:21]
	v_cndmask_b32_e64 v32, v32, v34, s[26:27]
	v_cndmask_b32_e32 v34, v34, v40, vcc
	v_sub_f32_e32 v32, v32, v34
	v_mul_f32_e32 v32, 0x3fb8aa3b, v32
	v_exp_f32_e32 v32, v32
	v_cndmask_b32_e64 v33, v33, 2, s[18:19]
	v_cndmask_b32_e64 v33, v33, 3, s[16:17]
	v_cndmask_b32_e64 v33, v33, 4, s[14:15]
	v_add_f32_e32 v32, 1.0, v32
	v_div_scale_f32 v34, s[14:15], v32, v32, 1.0
	v_rcp_f32_e32 v35, v34
	v_cndmask_b32_e64 v33, v33, 5, s[12:13]
	v_cndmask_b32_e64 v33, 6, v33, s[24:25]
	v_cndmask_b32_e64 v36, v33, 7, s[26:27]
	v_fma_f32 v33, -v34, v35, 1.0
	v_fmac_f32_e32 v35, v33, v35
	v_div_scale_f32 v33, vcc, 1.0, v32, 1.0
	v_mul_f32_e32 v37, v33, v35
	v_fma_f32 v38, -v34, v37, v33
	v_fmac_f32_e32 v37, v38, v35
	v_fma_f32 v33, -v34, v37, v33
	v_div_fmas_f32 v33, v33, v35, v37
	s_lshl_b64 s[12:13], s[38:39], 2
	v_div_fixup_f32 v32, v33, v32, 1.0
	v_lshl_add_u32 v33, v36, 8, v41
	s_add_u32 s12, s51, s12
	global_store_dword v51, v33, s[40:41]
	s_addc_u32 s13, s52, s13
	v_sub_f32_e32 v33, 1.0, v32
	global_store_dwordx2 v51, v[32:33], s[12:13]
	v_lshl_add_u32 v32, v41, 2, 0
	ds_add_u32 v32, v63 offset:32768
	v_lshl_add_u32 v32, v36, 2, 0
	ds_add_u32 v32, v63 offset:32768
	s_branch .LBB0_1895
